# ffn2 f32 epilogue de-serialised: invariant vectors once per tile, 16 row loads per half issued before LDS staging, unrolled chunks with counted waits (on top of sc1 GEMM epilogue stores)
# speedup vs baseline: 1.0110x; 1.0037x over previous
.LBB0_138:
	v_mov_b32_e32 v64, 0x2000
	v_sub_co_u32_e32 v64, vcc, s26, v64
	s_nop 0
	v_readfirstlane_b32 s14, v64
	s_lshr_b32 s14, s14, 11
	s_add_i32 s15, s14, 1
	s_and_b64 s[16:17], vcc, exec
	s_cselect_b32 s15, 0, s15
	s_mul_i32 s16, s82, 9
	s_add_i32 s15, s15, s16
	s_mul_hi_u32 s16, s15, 0x6000
	s_mulk_i32 s15, 0x6000
	s_add_u32 s15, s10, s15
	s_addc_u32 s41, s11, s16
	s_load_dwordx4 s[28:31], s[8:9], 0xe8
	s_load_dwordx2 s[16:17], s[8:9], 0x118
	s_lshl_b64 s[36:37], s[22:23], 2
	s_add_u32 s40, s15, s36
	s_addc_u32 s41, s41, s37
	s_lshl_b64 s[22:23], s[26:27], 12
	s_waitcnt lgkmcnt(0)
	s_add_u32 s15, s16, s22
	s_addc_u32 s17, s17, s23
	s_add_u32 s16, s15, s36
	s_addc_u32 s17, s17, s37
	s_lshl_b64 s[22:23], s[26:27], 3
	s_add_u32 s22, s46, s22
	s_addc_u32 s23, s49, s23
	s_add_u32 s15, s28, s20
	s_addc_u32 s26, s29, s21
	s_add_u32 s28, s15, s36
	v_mov_b32_e32 v72, v254
	s_addc_u32 s29, s26, s37
	s_add_u32 s15, s30, s20
	v_lshlrev_b32_e32 v64, 4, v72
	v_and_b32_e32 v148, 0x1f0, v64
	v_lshrrev_b32_e32 v64, 2, v72
	s_addc_u32 s26, s31, s21
	v_and_b32_e32 v64, 12, v64
	s_add_u32 s30, s15, s36
	v_and_b32_e32 v65, 0x4f, v72
	v_mul_u32_u24_e32 v64, 0x210, v64
	s_addc_u32 s31, s26, s37
	v_lshl_add_u32 v74, v65, 2, v64
	v_lshl_add_u64 v[64:65], s[16:17], 0, v[148:149]
	v_lshl_add_u64 v[66:67], s[40:41], 0, v[148:149]
	s_mov_b64 s[16:17], 0x5000
	s_mov_b32 s14, 0
	v_ashrrev_i32_e32 v73, 7, v72
	v_lshl_add_u64 v[66:67], v[66:67], 0, s[16:17]
	v_lshl_add_u64 v[68:69], s[28:29], 0, v[148:149]
	v_lshl_add_u64 v[70:71], s[30:31], 0, v[148:149]
	s_waitcnt vmcnt(0)
	global_load_dwordx4 v[160:163], v[66:67], off
	global_load_dwordx4 v[164:167], v[68:69], off
	global_load_dwordx4 v[168:171], v[70:71], off
	s_mov_b64 s[30:31], -1
.LBB0_139:
	v_cmp_eq_u32_e32 vcc, s14, v73
	s_lshl_b32 s15, s14, 6
	v_lshrrev_b32_e32 v75, 5, v72
	v_add_u32_e32 v76, s15, v75
	v_mov_b32_e32 v77, 0
	v_mad_u32_u24 v101, v75, s48, v148
	v_lshlrev_b64 v[80:81], 12, v[76:77]
	v_lshlrev_b32_e32 v76, 1, v76
	v_lshl_add_u64 v[98:99], v[64:65], 0, v[80:81]
	v_lshl_add_u64 v[76:77], v[76:77], 2, s[22:23]
	s_mov_b64 s[16:17], 0x8000
	v_mov_b64_e32 v[82:83], v[98:99]
	global_load_dwordx2 v[172:173], v[76:77], off
	global_load_dwordx4 v[188:191], v[82:83], off
	v_lshl_add_u64 v[82:83], v[82:83], 0, s[16:17]
	global_load_dwordx2 v[174:175], v[76:77], off offset:64
	global_load_dwordx4 v[192:195], v[82:83], off
	v_lshl_add_u64 v[82:83], v[82:83], 0, s[16:17]
	global_load_dwordx2 v[176:177], v[76:77], off offset:128
	global_load_dwordx4 v[196:199], v[82:83], off
	v_lshl_add_u64 v[82:83], v[82:83], 0, s[16:17]
	global_load_dwordx2 v[178:179], v[76:77], off offset:192
	global_load_dwordx4 v[200:203], v[82:83], off
	v_lshl_add_u64 v[82:83], v[82:83], 0, s[16:17]
	global_load_dwordx2 v[180:181], v[76:77], off offset:256
	global_load_dwordx4 v[204:207], v[82:83], off
	v_lshl_add_u64 v[82:83], v[82:83], 0, s[16:17]
	global_load_dwordx2 v[182:183], v[76:77], off offset:320
	global_load_dwordx4 v[208:211], v[82:83], off
	v_lshl_add_u64 v[82:83], v[82:83], 0, s[16:17]
	global_load_dwordx2 v[184:185], v[76:77], off offset:384
	global_load_dwordx4 v[212:215], v[82:83], off
	v_lshl_add_u64 v[82:83], v[82:83], 0, s[16:17]
	global_load_dwordx2 v[186:187], v[76:77], off offset:448
	global_load_dwordx4 v[216:219], v[82:83], off
	s_barrier
	s_and_saveexec_b64 s[28:29], vcc
	s_cbranch_execz .LBB0_141
	v_add_u32_e32 v75, 0x8000, v74
	v_add_u32_e32 v76, 0x8400, v74
	ds_write2_b32 v75, v52, v48 offset1:16
	ds_write2_b32 v75, v53, v49 offset0:132 offset1:148
	ds_write2_b32 v76, v54, v50 offset0:8 offset1:24
	ds_write2_b32 v76, v55, v51 offset0:140 offset1:156
	ds_write2_b32 v75, v44, v40 offset0:32 offset1:48
	ds_write2_b32 v75, v45, v41 offset0:164 offset1:180
	ds_write2_b32 v76, v46, v42 offset0:40 offset1:56
	ds_write2_b32 v76, v47, v43 offset0:172 offset1:188
	v_add_u32_e32 v75, 0xa000, v74
	v_add_u32_e32 v76, 0xa400, v74
	ds_write2_b32 v75, v36, v32 offset0:64 offset1:80
	ds_write2_b32 v75, v37, v33 offset0:196 offset1:212
	ds_write2_b32 v76, v38, v34 offset0:72 offset1:88
	ds_write2_b32 v76, v39, v35 offset0:204 offset1:220
	ds_write2_b32 v75, v28, v24 offset0:96 offset1:112
	ds_write2_b32 v75, v29, v25 offset0:228 offset1:244
	ds_write2_b32 v76, v30, v26 offset0:104 offset1:120
	ds_write2_b32 v76, v31, v27 offset0:236 offset1:252
	v_add_u32_e32 v75, 0xc000, v74
	v_add_u32_e32 v76, 0xc400, v74
	v_add_u32_e32 v77, 0xc800, v74
	ds_write2_b32 v75, v20, v16 offset0:128 offset1:144
	ds_write2_b32 v76, v21, v17 offset0:4 offset1:20
	ds_write2_b32 v76, v22, v18 offset0:136 offset1:152
	ds_write2_b32 v77, v23, v19 offset0:12 offset1:28
	ds_write2_b32 v75, v12, v8 offset0:160 offset1:176
	ds_write2_b32 v76, v13, v9 offset0:36 offset1:52
	ds_write2_b32 v76, v14, v10 offset0:168 offset1:184
	ds_write2_b32 v77, v15, v11 offset0:44 offset1:60
	v_add_u32_e32 v75, 0xe000, v74
	v_add_u32_e32 v76, 0xe400, v74
	v_add_u32_e32 v77, 0xe800, v74
	ds_write2_b32 v75, v4, v0 offset0:192 offset1:208
	ds_write2_b32 v76, v5, v1 offset0:68 offset1:84
	ds_write2_b32 v76, v6, v2 offset0:200 offset1:216
	ds_write2_b32 v77, v7, v3 offset0:76 offset1:92
	ds_write2_b32 v75, v56, v60 offset0:224 offset1:240
	ds_write2_b32 v76, v57, v61 offset0:100 offset1:116
	ds_write2_b32 v76, v58, v62 offset0:232 offset1:248
	ds_write2_b32 v77, v59, v63 offset0:108 offset1:124

.LBB0_142:
	ds_read_b128 v[220:223], v101 offset:32768
	ds_read_b128 v[224:227], v101 offset:36992
	ds_read_b128 v[228:231], v101 offset:41216
	ds_read_b128 v[232:235], v101 offset:45440
	ds_read_b128 v[236:239], v101 offset:49664
	ds_read_b128 v[240:243], v101 offset:53888
	ds_read_b128 v[244:247], v101 offset:58112
	ds_read_b128 v[248:251], v101 offset:62336
	s_waitcnt vmcnt(14)
	v_pk_add_f32 v[188:189], v[188:189], v[172:173] op_sel_hi:[1,0] neg_lo:[0,1] neg_hi:[0,1]
	s_nop 0
	v_pk_mul_f32 v[188:189], v[172:173], v[188:189] op_sel:[1,0]
	s_nop 0
	v_pk_fma_f32 v[188:189], v[188:189], v[164:165], v[168:169]
	s_nop 0
	v_pk_mul_f32 v[188:189], v[188:189], s[54:55] op_sel_hi:[1,0]
	s_waitcnt lgkmcnt(7)
	v_pk_fma_f32 v[220:221], v[220:221], v[160:161], v[188:189]
	v_pk_add_f32 v[190:191], v[190:191], v[172:173] op_sel_hi:[1,0] neg_lo:[0,1] neg_hi:[0,1]
	s_nop 0
	v_pk_mul_f32 v[190:191], v[172:173], v[190:191] op_sel:[1,0]
	s_nop 0
	v_pk_fma_f32 v[190:191], v[190:191], v[166:167], v[170:171]
	s_nop 0
	v_pk_mul_f32 v[190:191], v[190:191], s[54:55] op_sel_hi:[1,0]
	s_nop 0
	v_pk_fma_f32 v[222:223], v[222:223], v[162:163], v[190:191]
	global_store_dwordx4 v[98:99], v[220:223], off sc1
	v_lshl_add_u64 v[98:99], v[98:99], 0, s[16:17]
	s_waitcnt vmcnt(13)
	v_pk_add_f32 v[192:193], v[192:193], v[174:175] op_sel_hi:[1,0] neg_lo:[0,1] neg_hi:[0,1]
	s_nop 0
	v_pk_mul_f32 v[192:193], v[174:175], v[192:193] op_sel:[1,0]
	s_nop 0
	v_pk_fma_f32 v[192:193], v[192:193], v[164:165], v[168:169]
	s_nop 0
	v_pk_mul_f32 v[192:193], v[192:193], s[54:55] op_sel_hi:[1,0]
	s_waitcnt lgkmcnt(6)
	v_pk_fma_f32 v[224:225], v[224:225], v[160:161], v[192:193]
	v_pk_add_f32 v[194:195], v[194:195], v[174:175] op_sel_hi:[1,0] neg_lo:[0,1] neg_hi:[0,1]
	s_nop 0
	v_pk_mul_f32 v[194:195], v[174:175], v[194:195] op_sel:[1,0]
	s_nop 0
	v_pk_fma_f32 v[194:195], v[194:195], v[166:167], v[170:171]
	s_nop 0
	v_pk_mul_f32 v[194:195], v[194:195], s[54:55] op_sel_hi:[1,0]
	s_nop 0
	v_pk_fma_f32 v[226:227], v[226:227], v[162:163], v[194:195]
	global_store_dwordx4 v[98:99], v[224:227], off sc1
	v_lshl_add_u64 v[98:99], v[98:99], 0, s[16:17]
	s_waitcnt vmcnt(12)
	v_pk_add_f32 v[196:197], v[196:197], v[176:177] op_sel_hi:[1,0] neg_lo:[0,1] neg_hi:[0,1]
	s_nop 0
	v_pk_mul_f32 v[196:197], v[176:177], v[196:197] op_sel:[1,0]
	s_nop 0
	v_pk_fma_f32 v[196:197], v[196:197], v[164:165], v[168:169]
	s_nop 0
	v_pk_mul_f32 v[196:197], v[196:197], s[54:55] op_sel_hi:[1,0]
	s_waitcnt lgkmcnt(5)
	v_pk_fma_f32 v[228:229], v[228:229], v[160:161], v[196:197]
	v_pk_add_f32 v[198:199], v[198:199], v[176:177] op_sel_hi:[1,0] neg_lo:[0,1] neg_hi:[0,1]
	s_nop 0
	v_pk_mul_f32 v[198:199], v[176:177], v[198:199] op_sel:[1,0]
	s_nop 0
	v_pk_fma_f32 v[198:199], v[198:199], v[166:167], v[170:171]
	s_nop 0
	v_pk_mul_f32 v[198:199], v[198:199], s[54:55] op_sel_hi:[1,0]
	s_nop 0
	v_pk_fma_f32 v[230:231], v[230:231], v[162:163], v[198:199]
	global_store_dwordx4 v[98:99], v[228:231], off sc1
	v_lshl_add_u64 v[98:99], v[98:99], 0, s[16:17]
	s_waitcnt vmcnt(11)
	v_pk_add_f32 v[200:201], v[200:201], v[178:179] op_sel_hi:[1,0] neg_lo:[0,1] neg_hi:[0,1]
	s_nop 0
	v_pk_mul_f32 v[200:201], v[178:179], v[200:201] op_sel:[1,0]
	s_nop 0
	v_pk_fma_f32 v[200:201], v[200:201], v[164:165], v[168:169]
	s_nop 0
	v_pk_mul_f32 v[200:201], v[200:201], s[54:55] op_sel_hi:[1,0]
	s_waitcnt lgkmcnt(4)
	v_pk_fma_f32 v[232:233], v[232:233], v[160:161], v[200:201]
	v_pk_add_f32 v[202:203], v[202:203], v[178:179] op_sel_hi:[1,0] neg_lo:[0,1] neg_hi:[0,1]
	s_nop 0
	v_pk_mul_f32 v[202:203], v[178:179], v[202:203] op_sel:[1,0]
	s_nop 0
	v_pk_fma_f32 v[202:203], v[202:203], v[166:167], v[170:171]
	s_nop 0
	v_pk_mul_f32 v[202:203], v[202:203], s[54:55] op_sel_hi:[1,0]
	s_nop 0
	v_pk_fma_f32 v[234:235], v[234:235], v[162:163], v[202:203]
	global_store_dwordx4 v[98:99], v[232:235], off sc1
	v_lshl_add_u64 v[98:99], v[98:99], 0, s[16:17]
	s_waitcnt vmcnt(10)
	v_pk_add_f32 v[204:205], v[204:205], v[180:181] op_sel_hi:[1,0] neg_lo:[0,1] neg_hi:[0,1]
	s_nop 0
	v_pk_mul_f32 v[204:205], v[180:181], v[204:205] op_sel:[1,0]
	s_nop 0
	v_pk_fma_f32 v[204:205], v[204:205], v[164:165], v[168:169]
	s_nop 0
	v_pk_mul_f32 v[204:205], v[204:205], s[54:55] op_sel_hi:[1,0]
	s_waitcnt lgkmcnt(3)
	v_pk_fma_f32 v[236:237], v[236:237], v[160:161], v[204:205]
	v_pk_add_f32 v[206:207], v[206:207], v[180:181] op_sel_hi:[1,0] neg_lo:[0,1] neg_hi:[0,1]
	s_nop 0
	v_pk_mul_f32 v[206:207], v[180:181], v[206:207] op_sel:[1,0]
	s_nop 0
	v_pk_fma_f32 v[206:207], v[206:207], v[166:167], v[170:171]
	s_nop 0
	v_pk_mul_f32 v[206:207], v[206:207], s[54:55] op_sel_hi:[1,0]
	s_nop 0
	v_pk_fma_f32 v[238:239], v[238:239], v[162:163], v[206:207]
	global_store_dwordx4 v[98:99], v[236:239], off sc1
	v_lshl_add_u64 v[98:99], v[98:99], 0, s[16:17]
	s_waitcnt vmcnt(9)
	v_pk_add_f32 v[208:209], v[208:209], v[182:183] op_sel_hi:[1,0] neg_lo:[0,1] neg_hi:[0,1]
	s_nop 0
	v_pk_mul_f32 v[208:209], v[182:183], v[208:209] op_sel:[1,0]
	s_nop 0
	v_pk_fma_f32 v[208:209], v[208:209], v[164:165], v[168:169]
	s_nop 0
	v_pk_mul_f32 v[208:209], v[208:209], s[54:55] op_sel_hi:[1,0]
	s_waitcnt lgkmcnt(2)
	v_pk_fma_f32 v[240:241], v[240:241], v[160:161], v[208:209]
	v_pk_add_f32 v[210:211], v[210:211], v[182:183] op_sel_hi:[1,0] neg_lo:[0,1] neg_hi:[0,1]
	s_nop 0
	v_pk_mul_f32 v[210:211], v[182:183], v[210:211] op_sel:[1,0]
	s_nop 0
	v_pk_fma_f32 v[210:211], v[210:211], v[166:167], v[170:171]
	s_nop 0
	v_pk_mul_f32 v[210:211], v[210:211], s[54:55] op_sel_hi:[1,0]
	s_nop 0
	v_pk_fma_f32 v[242:243], v[242:243], v[162:163], v[210:211]
	global_store_dwordx4 v[98:99], v[240:243], off sc1
	v_lshl_add_u64 v[98:99], v[98:99], 0, s[16:17]
	s_waitcnt vmcnt(8)
	v_pk_add_f32 v[212:213], v[212:213], v[184:185] op_sel_hi:[1,0] neg_lo:[0,1] neg_hi:[0,1]
	s_nop 0
	v_pk_mul_f32 v[212:213], v[184:185], v[212:213] op_sel:[1,0]
	s_nop 0
	v_pk_fma_f32 v[212:213], v[212:213], v[164:165], v[168:169]
	s_nop 0
	v_pk_mul_f32 v[212:213], v[212:213], s[54:55] op_sel_hi:[1,0]
	s_waitcnt lgkmcnt(1)
	v_pk_fma_f32 v[244:245], v[244:245], v[160:161], v[212:213]
	v_pk_add_f32 v[214:215], v[214:215], v[184:185] op_sel_hi:[1,0] neg_lo:[0,1] neg_hi:[0,1]
	s_nop 0
	v_pk_mul_f32 v[214:215], v[184:185], v[214:215] op_sel:[1,0]
	s_nop 0
	v_pk_fma_f32 v[214:215], v[214:215], v[166:167], v[170:171]
	s_nop 0
	v_pk_mul_f32 v[214:215], v[214:215], s[54:55] op_sel_hi:[1,0]
	s_nop 0
	v_pk_fma_f32 v[246:247], v[246:247], v[162:163], v[214:215]
	global_store_dwordx4 v[98:99], v[244:247], off sc1
	v_lshl_add_u64 v[98:99], v[98:99], 0, s[16:17]
	s_waitcnt vmcnt(7)
	v_pk_add_f32 v[216:217], v[216:217], v[186:187] op_sel_hi:[1,0] neg_lo:[0,1] neg_hi:[0,1]
	s_nop 0
	v_pk_mul_f32 v[216:217], v[186:187], v[216:217] op_sel:[1,0]
	s_nop 0
	v_pk_fma_f32 v[216:217], v[216:217], v[164:165], v[168:169]
	s_nop 0
	v_pk_mul_f32 v[216:217], v[216:217], s[54:55] op_sel_hi:[1,0]
	s_waitcnt lgkmcnt(0)
	v_pk_fma_f32 v[248:249], v[248:249], v[160:161], v[216:217]
	v_pk_add_f32 v[218:219], v[218:219], v[186:187] op_sel_hi:[1,0] neg_lo:[0,1] neg_hi:[0,1]
	s_nop 0
	v_pk_mul_f32 v[218:219], v[186:187], v[218:219] op_sel:[1,0]
	s_nop 0
	v_pk_fma_f32 v[218:219], v[218:219], v[166:167], v[170:171]
	s_nop 0
	v_pk_mul_f32 v[218:219], v[218:219], s[54:55] op_sel_hi:[1,0]
	s_nop 0
	v_pk_fma_f32 v[250:251], v[250:251], v[162:163], v[218:219]
	global_store_dwordx4 v[98:99], v[248:251], off sc1
	s_mov_b32 s14, 1
	s_mov_b64 s[30:31], 0
	s_and_b64 vcc, exec, s[28:29]
	s_cbranch_vccz .LBB0_139
	s_mov_b64 s[22:23], -1
	s_and_b64 vcc, exec, s[6:7]
	s_mov_b32 s14, s56
	s_cbranch_vccz .LBB0_117
